# hyena units: all conv-input loads of a channel issued early as cache-warming loads (latent + context)
# speedup vs baseline: 1.0159x; 1.0012x over previous
.LBB0_464:
	s_or_b64 exec, exec, s[2:3]
	s_lshl_b32 s2, s34, 9
	s_mov_b32 s3, s35
	v_lshl_add_u64 v[10:11], v[32:33], 0, s[2:3]
	v_mov_b32_e32 v35, v0
	v_lshl_add_u64 v[10:11], v[10:11], 0, v[34:35]
	v_mov_b32_e32 v37, v0
	v_lshl_add_u64 v[10:11], v[10:11], 0, v[36:37]
	s_mov_b64 s[2:3], 0xc0000
	v_lshl_add_u64 v[12:13], v[10:11], 0, s[2:3]
	s_mov_b32 s2, 0xc0000
	v_add_co_u32_e32 v10, vcc, s2, v10
	s_lshl_b64 s[22:23], s[34:35], 9
	s_nop 0
	v_addc_co_u32_e32 v11, vcc, 0, v11, vcc
	v_readlane_b32 s2, v254, 14
	global_load_dwordx2 v[40:41], v[10:11], off
	global_load_dwordx2 v[38:39], v[12:13], off offset:32
	global_load_dwordx2 v[16:17], v[12:13], off offset:64
	global_load_dwordx2 v[14:15], v[12:13], off offset:96
	v_or_b32_e32 v11, s23, v29
	v_or_b32_e32 v10, s22, v28
	v_readlane_b32 s3, v254, 15
	s_barrier
	s_nop 0
	v_lshl_add_u64 v[132:133], s[2:3], 0, v[10:11]
	v_or_b32_e32 v135, s23, v31
	v_or_b32_e32 v134, s22, v30
	v_lshl_add_u64 v[134:135], s[2:3], 0, v[134:135]
	v_mov_b64_e32 v[136:137], v[132:133]
	v_lshl_add_u64 v[138:139], v[20:21], 1, v[136:137]
	v_lshl_add_u64 v[140:141], v[22:23], 1, v[136:137]
	global_load_dword v144, v[138:139], off
	global_load_dword v145, v[138:139], off offset:16
	global_load_ushort v146, v[140:141], off offset:-2
	s_mov_b64 s[100:101], 0x40000
	v_lshl_add_u64 v[136:137], v[132:133], 0, s[100:101]
	v_lshl_add_u64 v[138:139], v[20:21], 1, v[136:137]
	v_lshl_add_u64 v[140:141], v[22:23], 1, v[136:137]
	global_load_dword v147, v[138:139], off
	global_load_dword v148, v[138:139], off offset:16
	global_load_ushort v149, v[140:141], off offset:-2
	s_mov_b64 s[100:101], 0x80000
	v_lshl_add_u64 v[136:137], v[132:133], 0, s[100:101]
	v_lshl_add_u64 v[138:139], v[20:21], 1, v[136:137]
	v_lshl_add_u64 v[140:141], v[22:23], 1, v[136:137]
	global_load_dword v150, v[138:139], off
	global_load_dword v151, v[138:139], off offset:16
	global_load_ushort v152, v[140:141], off offset:-2
	v_mov_b64_e32 v[136:137], v[134:135]
	v_lshl_add_u64 v[138:139], v[24:25], 1, v[136:137]
	v_lshl_add_u64 v[140:141], v[26:27], 1, v[136:137]
	global_load_dword v153, v[138:139], off
	global_load_dword v154, v[138:139], off offset:16
	global_load_ushort v155, v[140:141], off offset:-2
	s_mov_b64 s[100:101], 0x40000
	v_lshl_add_u64 v[136:137], v[134:135], 0, s[100:101]
	v_lshl_add_u64 v[138:139], v[24:25], 1, v[136:137]
	v_lshl_add_u64 v[140:141], v[26:27], 1, v[136:137]
	global_load_dword v156, v[138:139], off
	global_load_dword v157, v[138:139], off offset:16
	global_load_ushort v158, v[140:141], off offset:-2
	s_mov_b64 s[100:101], 0x80000
	v_lshl_add_u64 v[136:137], v[134:135], 0, s[100:101]
	v_lshl_add_u64 v[138:139], v[24:25], 1, v[136:137]
	v_lshl_add_u64 v[140:141], v[26:27], 1, v[136:137]
	global_load_dword v159, v[138:139], off
	global_load_dword v160, v[138:139], off offset:16
	global_load_ushort v161, v[140:141], off offset:-2
	s_lshl_b64 s[100:101], s[34:35], 2
	s_add_u32 s100, s84, s100
	s_addc_u32 s101, s85, s101
	global_load_dword v162, v0, s[100:101]
	global_load_dword v163, v0, s[100:101] offset:2048
	s_add_u32 s100, s100, 0x1000
	s_addc_u32 s101, s101, 0
	global_load_dword v164, v0, s[100:101]
	s_lshl_b64 s[100:101], s[34:35], 2
	s_add_u32 s100, s11, s100
	s_addc_u32 s101, s96, s101
	global_load_dword v165, v224, s[100:101]
	global_load_dword v166, v0, s[100:101]
	global_load_dword v167, v225, s[100:101] offset:2048
	global_load_dword v168, v224, s[100:101] offset:2048
	global_load_dword v169, v0, s[100:101] offset:2048
	global_load_dword v170, v226, s[100:101]
	global_load_dword v171, v227, s[100:101]
	global_load_dword v172, v226, s[100:101] offset:2048
	s_add_u32 s100, s100, 0x1000
	s_addc_u32 s101, s101, 0
	global_load_dword v173, v0, s[100:101]
	v_lshl_add_u64 v[42:43], s[2:3], 0, v[10:11]
	v_lshl_add_u64 v[48:49], v[20:21], 1, v[42:43]
	global_load_dwordx4 v[10:13], v[48:49], off
	s_and_saveexec_b64 s[2:3], s[42:43]
	s_cbranch_execz .LBB0_466
	v_lshl_add_u64 v[44:45], v[22:23], 1, v[42:43]
	global_load_ushort v35, v[44:45], off offset:-2
	s_waitcnt vmcnt(0)
	v_lshlrev_b32_e32 v45, 16, v35
